# v31 plus: units that follow an epilogue get their own peeled first iteration whose first two counted waits no longer drain the epilogue's stores (SwiGLU phases)
# baseline (speedup 1.0000x reference)
; #define PG8_STAGE(bufoff, gbase, voff) do { _Pragma("unroll") for (int _i = 0; _i < 2; ++_i) \
;         __builtin_amdgcn_global_load_lds((const unsigned*)((const char*)(gbase) + (voff)[_i]), (PG8_LAS unsigned*)(lds + (bufoff) + ldsw + _i * 8192), 16, 0, 0); } while (0)
; #define PG8_LDA(dst, b, h) do { _Pragma("unroll") for (int m = 0; m < 4; ++m) _Pragma("unroll") for (int k = 0; k < 2; ++k) dst[m][k] = *(const PG8_LAS bf16x8*)(lds + PG8_SA(b, h) + aoff + m * 2048 + k * 1024); } while (0)
; #define PG8_LDB(dst, b, h) do { _Pragma("unroll") for (int n = 0; n < 2; ++n) _Pragma("unroll") for (int k = 0; k < 2; ++k) dst[n][k] = *(const PG8_LAS bf16x8*)(lds + PG8_SB(b, h) + boff + n * 2048 + k * 1024); } while (0)
; #define PG8_MMA(ai, bj, At, Bt) do { __builtin_amdgcn_s_setprio(1); _Pragma("unroll") for (int m = 0; m < 4; ++m) _Pragma("unroll") for (int n = 0; n < 2; ++n) _Pragma("unroll") for (int k = 0; k < 2; ++k) \
;         acc[ai][bj][m][n] = __builtin_amdgcn_mfma_f32_16x16x32_bf16(Bt[n][k], At[m][k], acc[ai][bj][m][n], 0, 0, 0); __builtin_amdgcn_s_setprio(0); } while (0)
; #define PG8_WAIT_V(n) asm volatile("s_waitcnt vmcnt(" #n ")" ::: "memory")
; #define PG8_WAIT_L(n) asm volatile("s_waitcnt lgkmcnt(" #n ")" ::: "memory")
; #define PG8_BAR __builtin_amdgcn_s_barrier()
; #define PG8_SCHED __builtin_amdgcn_sched_barrier(0)
; template <class Epi, class Sched, bool ALIGN_EPI = false, bool SP2 = false>
; __device__ __forceinline__ void gemm_phase(PG8_LAS unsigned char* lds, const Gemm g, const Sched& S, const Epi& E) {
;     ...
;             PG8_LDB(B0, 0, 0); PG8_LDB(B1, 0, 1); PG8_SCHED; PG8_LDA(At, 0, 0); PG8_STAGE(PG8_SA(1, 1), a1 + hstep, voffA);
;             PG8_WAIT_V(8); PG8_WAIT_L(0); PG8_BAR; PG8_MMA(0, 0, At, B0); PG8_MMA(0, 1, At, B1); PG8_BAR; PG8_SCHED;
;             PG8_LDA(At, 0, 1); PG8_STAGE(PG8_SB(0, 0), b2, voffB); PG8_STAGE(PG8_SB(0, 1), b2 + hstep, voffB); PG8_STAGE(PG8_SA(0, 0), a2, voffA);
;             PG8_WAIT_V(8); PG8_WAIT_L(0); PG8_BAR; PG8_MMA(1, 0, At, B0); PG8_MMA(1, 1, At, B1); PG8_BAR; PG8_SCHED;
.Lpeel_hoisted_0:
	ds_read_b128 v[154:157], v149
	ds_read_b128 v[158:161], v149 offset:1024
	ds_read_b128 v[162:165], v149 offset:2048
	ds_read_b128 v[166:169], v149 offset:3072
	ds_read_b128 v[170:173], v150
	ds_read_b128 v[174:177], v150 offset:1024
	ds_read_b128 v[178:181], v150 offset:2048
	ds_read_b128 v[182:185], v150 offset:3072
	s_add_u32 s40, s38, 0xfffc0080
	s_addc_u32 s41, s39, -1
	s_cmp_eq_u32 s68, 12
	s_cselect_b32 s43, s21, s41
	s_cselect_b32 s42, s64, s40
	s_cselect_b32 s41, s19, s67
	s_cselect_b32 s40, s65, s66
	v_lshl_add_u64 v[144:145], s[38:39], 0, v[136:137]
	s_add_i32 m0, s37, 0xc000
	ds_read_b128 v[186:189], v151
	ds_read_b128 v[190:193], v151 offset:1024
	ds_read_b128 v[194:197], v151 offset:2048
	ds_read_b128 v[198:201], v151 offset:3072
	ds_read_b128 v[202:205], v151 offset:4096
	ds_read_b128 v[206:209], v151 offset:5120
	ds_read_b128 v[210:213], v151 offset:6144
	ds_read_b128 v[214:217], v151 offset:7168
	global_load_lds_dwordx4 v[144:145], off
	v_lshl_add_u64 v[144:145], s[38:39], 0, v[138:139]
	s_add_i32 m0, s37, 0xe000
	s_nop 0
	global_load_lds_dwordx4 v[144:145], off
	s_waitcnt vmcnt(10)
	s_waitcnt lgkmcnt(0)
	s_barrier
	s_setprio 1
	v_mfma_f32_16x16x32_bf16 v[120:123], v[154:157], v[186:189], 0
	v_mfma_f32_16x16x32_bf16 v[116:119], v[162:165], v[186:189], 0
	v_mfma_f32_16x16x32_bf16 v[108:111], v[154:157], v[194:197], 0
	v_mfma_f32_16x16x32_bf16 v[100:103], v[162:165], v[194:197], 0
	v_mfma_f32_16x16x32_bf16 v[92:95], v[154:157], v[202:205], 0
	v_mfma_f32_16x16x32_bf16 v[84:87], v[162:165], v[202:205], 0
	v_mfma_f32_16x16x32_bf16 v[76:79], v[154:157], v[210:213], 0
	v_mfma_f32_16x16x32_bf16 v[68:71], v[162:165], v[210:213], 0
	v_mfma_f32_16x16x32_bf16 v[120:123], v[158:161], v[190:193], v[120:123]
	v_mfma_f32_16x16x32_bf16 v[116:119], v[166:169], v[190:193], v[116:119]
	v_mfma_f32_16x16x32_bf16 v[108:111], v[158:161], v[198:201], v[108:111]
	v_mfma_f32_16x16x32_bf16 v[100:103], v[166:169], v[198:201], v[100:103]
	v_mfma_f32_16x16x32_bf16 v[92:95], v[158:161], v[206:209], v[92:95]
	v_mfma_f32_16x16x32_bf16 v[84:87], v[166:169], v[206:209], v[84:87]
	v_mfma_f32_16x16x32_bf16 v[76:79], v[158:161], v[214:217], v[76:79]
	v_mfma_f32_16x16x32_bf16 v[68:71], v[166:169], v[214:217], v[68:71]
	v_mfma_f32_16x16x32_bf16 v[124:127], v[170:173], v[186:189], 0
	v_mfma_f32_16x16x32_bf16 v[112:115], v[178:181], v[186:189], 0
	v_mfma_f32_16x16x32_bf16 v[104:107], v[170:173], v[194:197], 0
	v_mfma_f32_16x16x32_bf16 v[96:99], v[178:181], v[194:197], 0
	v_mfma_f32_16x16x32_bf16 v[88:91], v[170:173], v[202:205], 0
	v_mfma_f32_16x16x32_bf16 v[80:83], v[178:181], v[202:205], 0
	v_mfma_f32_16x16x32_bf16 v[72:75], v[170:173], v[210:213], 0
	v_mfma_f32_16x16x32_bf16 v[64:67], v[178:181], v[210:213], 0
	v_mfma_f32_16x16x32_bf16 v[124:127], v[174:177], v[190:193], v[124:127]
	v_mfma_f32_16x16x32_bf16 v[112:115], v[182:185], v[190:193], v[112:115]
	v_mfma_f32_16x16x32_bf16 v[104:107], v[174:177], v[198:201], v[104:107]
	v_mfma_f32_16x16x32_bf16 v[96:99], v[182:185], v[198:201], v[96:99]
	v_mfma_f32_16x16x32_bf16 v[88:91], v[174:177], v[206:209], v[88:91]
	v_mfma_f32_16x16x32_bf16 v[80:83], v[182:185], v[206:209], v[80:83]
	v_mfma_f32_16x16x32_bf16 v[72:75], v[174:177], v[214:217], v[72:75]
	v_mfma_f32_16x16x32_bf16 v[64:67], v[182:185], v[214:217], v[64:67]
	s_barrier
	s_setprio 0
	s_add_i32 s69, s57, s48
	v_lshl_add_u64 v[144:145], s[40:41], 0, v[132:133]
	s_mov_b32 m0, s69
	ds_read_b128 v[186:189], v151 offset:16384
	ds_read_b128 v[190:193], v151 offset:17408
	ds_read_b128 v[194:197], v151 offset:18432
	ds_read_b128 v[198:201], v151 offset:19456
	ds_read_b128 v[202:205], v151 offset:20480
	ds_read_b128 v[206:209], v151 offset:21504
	ds_read_b128 v[210:213], v151 offset:22528
	ds_read_b128 v[214:217], v151 offset:23552
	global_load_lds_dwordx4 v[144:145], off
	s_add_i32 m0, s69, 0x2000
	s_add_u32 s70, s40, 0x40000
	v_lshl_add_u64 v[218:219], s[40:41], 0, v[128:129]
	s_addc_u32 s71, s41, 0
	s_add_i32 s69, s58, s48
	global_load_lds_dwordx4 v[218:219], off
	v_lshl_add_u64 v[220:221], s[70:71], 0, v[132:133]
	s_mov_b32 m0, s69
	v_lshl_add_u64 v[222:223], s[42:43], 0, v[130:131]
	global_load_lds_dwordx4 v[220:221], off
	v_lshl_add_u64 v[220:221], s[70:71], 0, v[128:129]
	s_add_i32 m0, s69, 0x2000
	s_nop 0
	global_load_lds_dwordx4 v[220:221], off
	v_lshl_add_u64 v[220:221], s[42:43], 0, v[134:135]
	s_mov_b32 m0, s37
	s_nop 0
	global_load_lds_dwordx4 v[220:221], off
	s_mov_b32 m0, s50
	s_nop 0
	global_load_lds_dwordx4 v[222:223], off
	s_waitcnt vmcnt(16)
	s_waitcnt lgkmcnt(0)
	s_barrier
	s_setprio 1
	v_mfma_f32_16x16x32_bf16 v[60:63], v[154:157], v[186:189], 0
	v_mfma_f32_16x16x32_bf16 v[52:55], v[162:165], v[186:189], 0
	v_mfma_f32_16x16x32_bf16 v[44:47], v[154:157], v[194:197], 0
	v_mfma_f32_16x16x32_bf16 v[36:39], v[162:165], v[194:197], 0
	v_mfma_f32_16x16x32_bf16 v[28:31], v[154:157], v[202:205], 0
	v_mfma_f32_16x16x32_bf16 v[20:23], v[162:165], v[202:205], 0
	v_mfma_f32_16x16x32_bf16 v[12:15], v[154:157], v[210:213], 0
	v_mfma_f32_16x16x32_bf16 v[4:7], v[162:165], v[210:213], 0
	v_mfma_f32_16x16x32_bf16 v[60:63], v[158:161], v[190:193], v[60:63]
	v_mfma_f32_16x16x32_bf16 v[52:55], v[166:169], v[190:193], v[52:55]
	v_mfma_f32_16x16x32_bf16 v[44:47], v[158:161], v[198:201], v[44:47]
	v_mfma_f32_16x16x32_bf16 v[36:39], v[166:169], v[198:201], v[36:39]
	v_mfma_f32_16x16x32_bf16 v[28:31], v[158:161], v[206:209], v[28:31]
	v_mfma_f32_16x16x32_bf16 v[20:23], v[166:169], v[206:209], v[20:23]
	v_mfma_f32_16x16x32_bf16 v[12:15], v[158:161], v[214:217], v[12:15]
	v_mfma_f32_16x16x32_bf16 v[4:7], v[166:169], v[214:217], v[4:7]
	v_mfma_f32_16x16x32_bf16 v[56:59], v[170:173], v[186:189], 0
	v_mfma_f32_16x16x32_bf16 v[48:51], v[178:181], v[186:189], 0
	v_mfma_f32_16x16x32_bf16 v[40:43], v[170:173], v[194:197], 0
	v_mfma_f32_16x16x32_bf16 v[32:35], v[178:181], v[194:197], 0
	v_mfma_f32_16x16x32_bf16 v[24:27], v[170:173], v[202:205], 0
	v_mfma_f32_16x16x32_bf16 v[16:19], v[178:181], v[202:205], 0
	v_mfma_f32_16x16x32_bf16 v[8:11], v[170:173], v[210:213], 0
	v_mfma_f32_16x16x32_bf16 v[0:3], v[178:181], v[210:213], 0
	v_mfma_f32_16x16x32_bf16 v[56:59], v[174:177], v[190:193], v[56:59]
	v_mfma_f32_16x16x32_bf16 v[48:51], v[182:185], v[190:193], v[48:51]
	v_mfma_f32_16x16x32_bf16 v[40:43], v[174:177], v[198:201], v[40:43]
	v_mfma_f32_16x16x32_bf16 v[32:35], v[182:185], v[198:201], v[32:35]
	v_mfma_f32_16x16x32_bf16 v[24:27], v[174:177], v[206:209], v[24:27]
	v_mfma_f32_16x16x32_bf16 v[16:19], v[182:185], v[206:209], v[16:19]
	v_mfma_f32_16x16x32_bf16 v[8:11], v[174:177], v[214:217], v[8:11]
	v_mfma_f32_16x16x32_bf16 v[0:3], v[182:185], v[214:217], v[0:3]
	s_barrier
; #define PG8_STAGE(bufoff, gbase, voff) do { _Pragma("unroll") for (int _i = 0; _i < 2; ++_i) \
;         __builtin_amdgcn_global_load_lds((const unsigned*)((const char*)(gbase) + (voff)[_i]), (PG8_LAS unsigned*)(lds + (bufoff) + ldsw + _i * 8192), 16, 0, 0); } while (0)
; #define PG8_LDA(dst, b, h) do { _Pragma("unroll") for (int m = 0; m < 4; ++m) _Pragma("unroll") for (int k = 0; k < 2; ++k) dst[m][k] = *(const PG8_LAS bf16x8*)(lds + PG8_SA(b, h) + aoff + m * 2048 + k * 1024); } while (0)
; #define PG8_LDB(dst, b, h) do { _Pragma("unroll") for (int n = 0; n < 2; ++n) _Pragma("unroll") for (int k = 0; k < 2; ++k) dst[n][k] = *(const PG8_LAS bf16x8*)(lds + PG8_SB(b, h) + boff + n * 2048 + k * 1024); } while (0)
; #define PG8_MMA(ai, bj, At, Bt) do { __builtin_amdgcn_s_setprio(1); _Pragma("unroll") for (int m = 0; m < 4; ++m) _Pragma("unroll") for (int n = 0; n < 2; ++n) _Pragma("unroll") for (int k = 0; k < 2; ++k) \
;         acc[ai][bj][m][n] = __builtin_amdgcn_mfma_f32_16x16x32_bf16(Bt[n][k], At[m][k], acc[ai][bj][m][n], 0, 0, 0); __builtin_amdgcn_s_setprio(0); } while (0)
; #define PG8_WAIT_V(n) asm volatile("s_waitcnt vmcnt(" #n ")" ::: "memory")
; #define PG8_WAIT_L(n) asm volatile("s_waitcnt lgkmcnt(" #n ")" ::: "memory")
; #define PG8_BAR __builtin_amdgcn_s_barrier()
; #define PG8_SCHED __builtin_amdgcn_sched_barrier(0)
; template <class Epi, class Sched, bool ALIGN_EPI = false, bool SP2 = false>
; __device__ __forceinline__ void gemm_phase(PG8_LAS unsigned char* lds, const Gemm g, const Sched& S, const Epi& E) {
;     ...
;             PG8_LDB(B0, 1, 0); PG8_LDB(B1, 1, 1); PG8_SCHED; PG8_LDA(At, 1, 0); PG8_STAGE(PG8_SA(0, 1), a2 + hstep, voffA);
;             PG8_WAIT_V(8); PG8_WAIT_L(0); PG8_BAR; PG8_MMA(0, 0, At, B0); PG8_MMA(0, 1, At, B1); PG8_BAR; PG8_SCHED;
;             PG8_LDA(At, 1, 1); PG8_STAGE(PG8_SB(1, 0), b3, voffB); PG8_STAGE(PG8_SB(1, 1), b3 + hstep, voffB); PG8_STAGE(PG8_SA(1, 0), a3, voffA);
;             PG8_WAIT_V(8); PG8_WAIT_L(0); PG8_BAR; PG8_MMA(1, 0, At, B0); PG8_MMA(1, 1, At, B1); PG8_BAR; PG8_SCHED;
	s_setprio 0
	s_add_i32 s69, 0, 0x18000
	v_add_u32_e32 v153, s69, v147
	s_add_i32 s70, 0, 0x1c000
	ds_read_b128 v[154:157], v153
	ds_read_b128 v[158:161], v153 offset:1024
	ds_read_b128 v[162:165], v153 offset:2048
	ds_read_b128 v[166:169], v153 offset:3072
	v_add_u32_e32 v153, s70, v147
	ds_read_b128 v[170:173], v153
	ds_read_b128 v[174:177], v153 offset:1024
	ds_read_b128 v[178:181], v153 offset:2048
	ds_read_b128 v[182:185], v153 offset:3072
	s_add_u32 s42, s42, 0x40000
	s_addc_u32 s43, s43, 0
	s_mov_b32 m0, s51
	v_lshl_add_u64 v[224:225], s[42:43], 0, v[134:135]
	ds_read_b128 v[186:189], v151 offset:32768
	ds_read_b128 v[190:193], v151 offset:33792
	ds_read_b128 v[194:197], v151 offset:34816
	ds_read_b128 v[198:201], v151 offset:35840
	ds_read_b128 v[202:205], v151 offset:36864
	ds_read_b128 v[206:209], v151 offset:37888
	ds_read_b128 v[210:213], v151 offset:38912
	ds_read_b128 v[214:217], v151 offset:39936
	global_load_lds_dwordx4 v[224:225], off
	v_lshl_add_u64 v[224:225], s[42:43], 0, v[130:131]
	s_mov_b32 m0, s52
	s_nop 0
	global_load_lds_dwordx4 v[224:225], off
	s_waitcnt vmcnt(8)
	s_waitcnt lgkmcnt(0)
	s_barrier
	s_setprio 1
	v_mfma_f32_16x16x32_bf16 v[120:123], v[154:157], v[186:189], v[120:123]
	v_mfma_f32_16x16x32_bf16 v[116:119], v[162:165], v[186:189], v[116:119]
	v_mfma_f32_16x16x32_bf16 v[108:111], v[154:157], v[194:197], v[108:111]
	v_mfma_f32_16x16x32_bf16 v[100:103], v[162:165], v[194:197], v[100:103]
	v_mfma_f32_16x16x32_bf16 v[92:95], v[154:157], v[202:205], v[92:95]
	v_mfma_f32_16x16x32_bf16 v[84:87], v[162:165], v[202:205], v[84:87]
	v_mfma_f32_16x16x32_bf16 v[76:79], v[154:157], v[210:213], v[76:79]
	v_mfma_f32_16x16x32_bf16 v[68:71], v[162:165], v[210:213], v[68:71]
	v_mfma_f32_16x16x32_bf16 v[120:123], v[158:161], v[190:193], v[120:123]
	v_mfma_f32_16x16x32_bf16 v[116:119], v[166:169], v[190:193], v[116:119]
	v_mfma_f32_16x16x32_bf16 v[108:111], v[158:161], v[198:201], v[108:111]
	v_mfma_f32_16x16x32_bf16 v[100:103], v[166:169], v[198:201], v[100:103]
	v_mfma_f32_16x16x32_bf16 v[92:95], v[158:161], v[206:209], v[92:95]
	v_mfma_f32_16x16x32_bf16 v[84:87], v[166:169], v[206:209], v[84:87]
	v_mfma_f32_16x16x32_bf16 v[76:79], v[158:161], v[214:217], v[76:79]
	v_mfma_f32_16x16x32_bf16 v[68:71], v[166:169], v[214:217], v[68:71]
	v_mfma_f32_16x16x32_bf16 v[124:127], v[170:173], v[186:189], v[124:127]
	v_mfma_f32_16x16x32_bf16 v[112:115], v[178:181], v[186:189], v[112:115]
	v_mfma_f32_16x16x32_bf16 v[104:107], v[170:173], v[194:197], v[104:107]
	v_mfma_f32_16x16x32_bf16 v[96:99], v[178:181], v[194:197], v[96:99]
	v_mfma_f32_16x16x32_bf16 v[88:91], v[170:173], v[202:205], v[88:91]
	v_mfma_f32_16x16x32_bf16 v[80:83], v[178:181], v[202:205], v[80:83]
	v_mfma_f32_16x16x32_bf16 v[72:75], v[170:173], v[210:213], v[72:75]
	v_mfma_f32_16x16x32_bf16 v[64:67], v[178:181], v[210:213], v[64:67]
	v_mfma_f32_16x16x32_bf16 v[124:127], v[174:177], v[190:193], v[124:127]
	v_mfma_f32_16x16x32_bf16 v[112:115], v[182:185], v[190:193], v[112:115]
	v_mfma_f32_16x16x32_bf16 v[104:107], v[174:177], v[198:201], v[104:107]
	v_mfma_f32_16x16x32_bf16 v[96:99], v[182:185], v[198:201], v[96:99]
	v_mfma_f32_16x16x32_bf16 v[88:91], v[174:177], v[206:209], v[88:91]
	v_mfma_f32_16x16x32_bf16 v[80:83], v[182:185], v[206:209], v[80:83]
	v_mfma_f32_16x16x32_bf16 v[72:75], v[174:177], v[214:217], v[72:75]
	v_mfma_f32_16x16x32_bf16 v[64:67], v[182:185], v[214:217], v[64:67]
	s_barrier
	s_setprio 0
	s_add_i32 s42, s69, s48
	v_lshl_add_u64 v[144:145], v[144:145], 0, s[14:15]
	s_mov_b32 m0, s42
	ds_read_b128 v[186:189], v151 offset:49152
	ds_read_b128 v[190:193], v151 offset:50176
	ds_read_b128 v[194:197], v151 offset:51200
	ds_read_b128 v[198:201], v151 offset:52224
	ds_read_b128 v[202:205], v151 offset:53248
	ds_read_b128 v[206:209], v151 offset:54272
	ds_read_b128 v[210:213], v151 offset:55296
	ds_read_b128 v[214:217], v151 offset:56320
	global_load_lds_dwordx4 v[144:145], off
	s_add_i32 m0, s42, 0x2000
	s_add_u32 s40, s40, 0x40080
	v_lshl_add_u64 v[144:145], v[218:219], 0, s[14:15]
	s_addc_u32 s41, s41, 0
	s_add_i32 s42, s70, s48
	global_load_lds_dwordx4 v[144:145], off
	v_lshl_add_u64 v[144:145], s[40:41], 0, v[132:133]
	s_mov_b32 m0, s42
	s_nop 0
	global_load_lds_dwordx4 v[144:145], off
	v_lshl_add_u64 v[144:145], s[40:41], 0, v[128:129]
	s_add_i32 m0, s42, 0x2000
	s_nop 0
	global_load_lds_dwordx4 v[144:145], off
	v_lshl_add_u64 v[144:145], v[220:221], 0, s[14:15]
	s_mov_b32 m0, s54
	s_nop 0
	global_load_lds_dwordx4 v[144:145], off
	v_lshl_add_u64 v[144:145], v[222:223], 0, s[14:15]
	s_mov_b32 m0, s55
	s_nop 0
	global_load_lds_dwordx4 v[144:145], off
	s_waitcnt vmcnt(8)
	s_waitcnt lgkmcnt(0)
	s_barrier
	s_setprio 1
	v_mfma_f32_16x16x32_bf16 v[60:63], v[154:157], v[186:189], v[60:63]
	v_mfma_f32_16x16x32_bf16 v[52:55], v[162:165], v[186:189], v[52:55]
	v_mfma_f32_16x16x32_bf16 v[44:47], v[154:157], v[194:197], v[44:47]
	v_mfma_f32_16x16x32_bf16 v[36:39], v[162:165], v[194:197], v[36:39]
	v_mfma_f32_16x16x32_bf16 v[28:31], v[154:157], v[202:205], v[28:31]
	v_mfma_f32_16x16x32_bf16 v[20:23], v[162:165], v[202:205], v[20:23]
	v_mfma_f32_16x16x32_bf16 v[12:15], v[154:157], v[210:213], v[12:15]
	v_mfma_f32_16x16x32_bf16 v[4:7], v[162:165], v[210:213], v[4:7]
	v_mfma_f32_16x16x32_bf16 v[60:63], v[158:161], v[190:193], v[60:63]
	v_mfma_f32_16x16x32_bf16 v[52:55], v[166:169], v[190:193], v[52:55]
	v_mfma_f32_16x16x32_bf16 v[44:47], v[158:161], v[198:201], v[44:47]
	v_mfma_f32_16x16x32_bf16 v[36:39], v[166:169], v[198:201], v[36:39]
	v_mfma_f32_16x16x32_bf16 v[28:31], v[158:161], v[206:209], v[28:31]
	v_mfma_f32_16x16x32_bf16 v[20:23], v[166:169], v[206:209], v[20:23]
	v_mfma_f32_16x16x32_bf16 v[12:15], v[158:161], v[214:217], v[12:15]
	v_mfma_f32_16x16x32_bf16 v[4:7], v[166:169], v[214:217], v[4:7]
	v_mfma_f32_16x16x32_bf16 v[56:59], v[170:173], v[186:189], v[56:59]
	v_mfma_f32_16x16x32_bf16 v[48:51], v[178:181], v[186:189], v[48:51]
	v_mfma_f32_16x16x32_bf16 v[40:43], v[170:173], v[194:197], v[40:43]
	v_mfma_f32_16x16x32_bf16 v[32:35], v[178:181], v[194:197], v[32:35]
	v_mfma_f32_16x16x32_bf16 v[24:27], v[170:173], v[202:205], v[24:27]
	v_mfma_f32_16x16x32_bf16 v[16:19], v[178:181], v[202:205], v[16:19]
	v_mfma_f32_16x16x32_bf16 v[8:11], v[170:173], v[210:213], v[8:11]
	v_mfma_f32_16x16x32_bf16 v[0:3], v[178:181], v[210:213], v[0:3]
	v_mfma_f32_16x16x32_bf16 v[56:59], v[174:177], v[190:193], v[56:59]
	v_mfma_f32_16x16x32_bf16 v[48:51], v[182:185], v[190:193], v[48:51]
	v_mfma_f32_16x16x32_bf16 v[40:43], v[174:177], v[198:201], v[40:43]
	v_mfma_f32_16x16x32_bf16 v[32:35], v[182:185], v[198:201], v[32:35]
	v_mfma_f32_16x16x32_bf16 v[24:27], v[174:177], v[206:209], v[24:27]
	v_mfma_f32_16x16x32_bf16 v[16:19], v[182:185], v[206:209], v[16:19]
	v_mfma_f32_16x16x32_bf16 v[8:11], v[174:177], v[214:217], v[8:11]
	v_mfma_f32_16x16x32_bf16 v[0:3], v[182:185], v[214:217], v[0:3]
	s_barrier
	s_setprio 0
	s_add_i32 s68, s68, 2
	s_add_u32 s38, s38, 0x100
	s_addc_u32 s39, s39, 0
	s_add_u32 s66, s66, 0x100
	s_addc_u32 s67, s67, 0

; #define PG8_STAGE(bufoff, gbase, voff) do { _Pragma("unroll") for (int _i = 0; _i < 2; ++_i) \
;         __builtin_amdgcn_global_load_lds((const unsigned*)((const char*)(gbase) + (voff)[_i]), (PG8_LAS unsigned*)(lds + (bufoff) + ldsw + _i * 8192), 16, 0, 0); } while (0)
; #define PG8_LDA(dst, b, h) do { _Pragma("unroll") for (int m = 0; m < 4; ++m) _Pragma("unroll") for (int k = 0; k < 2; ++k) dst[m][k] = *(const PG8_LAS bf16x8*)(lds + PG8_SA(b, h) + aoff + m * 2048 + k * 1024); } while (0)
; #define PG8_LDB(dst, b, h) do { _Pragma("unroll") for (int n = 0; n < 2; ++n) _Pragma("unroll") for (int k = 0; k < 2; ++k) dst[n][k] = *(const PG8_LAS bf16x8*)(lds + PG8_SB(b, h) + boff + n * 2048 + k * 1024); } while (0)
; #define PG8_MMA(ai, bj, At, Bt) do { __builtin_amdgcn_s_setprio(1); _Pragma("unroll") for (int m = 0; m < 4; ++m) _Pragma("unroll") for (int n = 0; n < 2; ++n) _Pragma("unroll") for (int k = 0; k < 2; ++k) \
;         acc[ai][bj][m][n] = __builtin_amdgcn_mfma_f32_16x16x32_bf16(Bt[n][k], At[m][k], acc[ai][bj][m][n], 0, 0, 0); __builtin_amdgcn_s_setprio(0); } while (0)
; #define PG8_WAIT_V(n) asm volatile("s_waitcnt vmcnt(" #n ")" ::: "memory")
; #define PG8_WAIT_L(n) asm volatile("s_waitcnt lgkmcnt(" #n ")" ::: "memory")
; #define PG8_BAR __builtin_amdgcn_s_barrier()
; #define PG8_SCHED __builtin_amdgcn_sched_barrier(0)
; template <class Epi, class Sched, bool ALIGN_EPI = false, bool SP2 = false>
; __device__ __forceinline__ void gemm_phase(PG8_LAS unsigned char* lds, const Gemm g, const Sched& S, const Epi& E) {
;     ...
;             PG8_LDB(B0, 0, 0); PG8_LDB(B1, 0, 1); PG8_SCHED; PG8_LDA(At, 0, 0); PG8_STAGE(PG8_SA(1, 1), a1 + hstep, voffA);
;             PG8_WAIT_V(8); PG8_WAIT_L(0); PG8_BAR; PG8_MMA(0, 0, At, B0); PG8_MMA(0, 1, At, B1); PG8_BAR; PG8_SCHED;
;             PG8_LDA(At, 0, 1); PG8_STAGE(PG8_SB(0, 0), b2, voffB); PG8_STAGE(PG8_SB(0, 1), b2 + hstep, voffB); PG8_STAGE(PG8_SA(0, 0), a2, voffA);
;             PG8_WAIT_V(8); PG8_WAIT_L(0); PG8_BAR; PG8_MMA(1, 0, At, B0); PG8_MMA(1, 1, At, B1); PG8_BAR; PG8_SCHED;
.Lpeel_hoisted_1:
	ds_read_b128 v[154:157], v149
	ds_read_b128 v[158:161], v149 offset:1024
	ds_read_b128 v[162:165], v149 offset:2048
	ds_read_b128 v[166:169], v149 offset:3072
	ds_read_b128 v[170:173], v150
	ds_read_b128 v[174:177], v150 offset:1024
	ds_read_b128 v[178:181], v150 offset:2048
	ds_read_b128 v[182:185], v150 offset:3072
	s_add_u32 s40, s38, 0xfffc0080
	s_addc_u32 s41, s39, -1
	s_cmp_eq_u32 s68, 12
	s_cselect_b32 s43, s21, s41
	s_cselect_b32 s42, s64, s40
	s_cselect_b32 s41, s19, s67
	s_cselect_b32 s40, s65, s66
	v_lshl_add_u64 v[144:145], s[38:39], 0, v[136:137]
	s_add_i32 m0, s37, 0xc000
	ds_read_b128 v[186:189], v151
	ds_read_b128 v[190:193], v151 offset:1024
	ds_read_b128 v[194:197], v151 offset:2048
	ds_read_b128 v[198:201], v151 offset:3072
	ds_read_b128 v[202:205], v151 offset:4096
	ds_read_b128 v[206:209], v151 offset:5120
	ds_read_b128 v[210:213], v151 offset:6144
	ds_read_b128 v[214:217], v151 offset:7168
	global_load_lds_dwordx4 v[144:145], off
	v_lshl_add_u64 v[144:145], s[38:39], 0, v[138:139]
	s_add_i32 m0, s37, 0xe000
	s_nop 0
	global_load_lds_dwordx4 v[144:145], off
	s_waitcnt vmcnt(10)
	s_waitcnt lgkmcnt(0)
	s_barrier
	s_setprio 1
	v_mfma_f32_16x16x32_bf16 v[120:123], v[154:157], v[186:189], 0
	v_mfma_f32_16x16x32_bf16 v[116:119], v[162:165], v[186:189], 0
	v_mfma_f32_16x16x32_bf16 v[108:111], v[154:157], v[194:197], 0
	v_mfma_f32_16x16x32_bf16 v[100:103], v[162:165], v[194:197], 0
	v_mfma_f32_16x16x32_bf16 v[92:95], v[154:157], v[202:205], 0
	v_mfma_f32_16x16x32_bf16 v[84:87], v[162:165], v[202:205], 0
	v_mfma_f32_16x16x32_bf16 v[76:79], v[154:157], v[210:213], 0
	v_mfma_f32_16x16x32_bf16 v[68:71], v[162:165], v[210:213], 0
	v_mfma_f32_16x16x32_bf16 v[120:123], v[158:161], v[190:193], v[120:123]
	v_mfma_f32_16x16x32_bf16 v[116:119], v[166:169], v[190:193], v[116:119]
	v_mfma_f32_16x16x32_bf16 v[108:111], v[158:161], v[198:201], v[108:111]
	v_mfma_f32_16x16x32_bf16 v[100:103], v[166:169], v[198:201], v[100:103]
	v_mfma_f32_16x16x32_bf16 v[92:95], v[158:161], v[206:209], v[92:95]
	v_mfma_f32_16x16x32_bf16 v[84:87], v[166:169], v[206:209], v[84:87]
	v_mfma_f32_16x16x32_bf16 v[76:79], v[158:161], v[214:217], v[76:79]
	v_mfma_f32_16x16x32_bf16 v[68:71], v[166:169], v[214:217], v[68:71]
	v_mfma_f32_16x16x32_bf16 v[124:127], v[170:173], v[186:189], 0
	v_mfma_f32_16x16x32_bf16 v[112:115], v[178:181], v[186:189], 0
	v_mfma_f32_16x16x32_bf16 v[104:107], v[170:173], v[194:197], 0
	v_mfma_f32_16x16x32_bf16 v[96:99], v[178:181], v[194:197], 0
	v_mfma_f32_16x16x32_bf16 v[88:91], v[170:173], v[202:205], 0
	v_mfma_f32_16x16x32_bf16 v[80:83], v[178:181], v[202:205], 0
	v_mfma_f32_16x16x32_bf16 v[72:75], v[170:173], v[210:213], 0
	v_mfma_f32_16x16x32_bf16 v[64:67], v[178:181], v[210:213], 0
	v_mfma_f32_16x16x32_bf16 v[124:127], v[174:177], v[190:193], v[124:127]
	v_mfma_f32_16x16x32_bf16 v[112:115], v[182:185], v[190:193], v[112:115]
	v_mfma_f32_16x16x32_bf16 v[104:107], v[174:177], v[198:201], v[104:107]
	v_mfma_f32_16x16x32_bf16 v[96:99], v[182:185], v[198:201], v[96:99]
	v_mfma_f32_16x16x32_bf16 v[88:91], v[174:177], v[206:209], v[88:91]
	v_mfma_f32_16x16x32_bf16 v[80:83], v[182:185], v[206:209], v[80:83]
	v_mfma_f32_16x16x32_bf16 v[72:75], v[174:177], v[214:217], v[72:75]
	v_mfma_f32_16x16x32_bf16 v[64:67], v[182:185], v[214:217], v[64:67]
	s_barrier
	s_setprio 0
	s_add_i32 s69, s57, s48
	v_lshl_add_u64 v[144:145], s[40:41], 0, v[132:133]
	s_mov_b32 m0, s69
	ds_read_b128 v[186:189], v151 offset:16384
	ds_read_b128 v[190:193], v151 offset:17408
	ds_read_b128 v[194:197], v151 offset:18432
	ds_read_b128 v[198:201], v151 offset:19456
	ds_read_b128 v[202:205], v151 offset:20480
	ds_read_b128 v[206:209], v151 offset:21504
	ds_read_b128 v[210:213], v151 offset:22528
	ds_read_b128 v[214:217], v151 offset:23552
	global_load_lds_dwordx4 v[144:145], off
	s_add_i32 m0, s69, 0x2000
	s_add_u32 s70, s40, 0x40000
	v_lshl_add_u64 v[218:219], s[40:41], 0, v[128:129]
	s_addc_u32 s71, s41, 0
	s_add_i32 s69, s58, s48
	global_load_lds_dwordx4 v[218:219], off
	v_lshl_add_u64 v[220:221], s[70:71], 0, v[132:133]
	s_mov_b32 m0, s69
	v_lshl_add_u64 v[222:223], s[42:43], 0, v[130:131]
	global_load_lds_dwordx4 v[220:221], off
	v_lshl_add_u64 v[220:221], s[70:71], 0, v[128:129]
	s_add_i32 m0, s69, 0x2000
	s_nop 0
	global_load_lds_dwordx4 v[220:221], off
	v_lshl_add_u64 v[220:221], s[42:43], 0, v[134:135]
	s_mov_b32 m0, s37
	s_nop 0
	global_load_lds_dwordx4 v[220:221], off
	s_mov_b32 m0, s50
	s_nop 0
	global_load_lds_dwordx4 v[222:223], off
	s_waitcnt vmcnt(16)
	s_waitcnt lgkmcnt(0)
	s_barrier
	s_setprio 1
	v_mfma_f32_16x16x32_bf16 v[60:63], v[154:157], v[186:189], 0
	v_mfma_f32_16x16x32_bf16 v[52:55], v[162:165], v[186:189], 0
	v_mfma_f32_16x16x32_bf16 v[44:47], v[154:157], v[194:197], 0
	v_mfma_f32_16x16x32_bf16 v[36:39], v[162:165], v[194:197], 0
	v_mfma_f32_16x16x32_bf16 v[28:31], v[154:157], v[202:205], 0
	v_mfma_f32_16x16x32_bf16 v[20:23], v[162:165], v[202:205], 0
	v_mfma_f32_16x16x32_bf16 v[12:15], v[154:157], v[210:213], 0
	v_mfma_f32_16x16x32_bf16 v[4:7], v[162:165], v[210:213], 0
	v_mfma_f32_16x16x32_bf16 v[60:63], v[158:161], v[190:193], v[60:63]
	v_mfma_f32_16x16x32_bf16 v[52:55], v[166:169], v[190:193], v[52:55]
	v_mfma_f32_16x16x32_bf16 v[44:47], v[158:161], v[198:201], v[44:47]
	v_mfma_f32_16x16x32_bf16 v[36:39], v[166:169], v[198:201], v[36:39]
	v_mfma_f32_16x16x32_bf16 v[28:31], v[158:161], v[206:209], v[28:31]
	v_mfma_f32_16x16x32_bf16 v[20:23], v[166:169], v[206:209], v[20:23]
	v_mfma_f32_16x16x32_bf16 v[12:15], v[158:161], v[214:217], v[12:15]
	v_mfma_f32_16x16x32_bf16 v[4:7], v[166:169], v[214:217], v[4:7]
	v_mfma_f32_16x16x32_bf16 v[56:59], v[170:173], v[186:189], 0
	v_mfma_f32_16x16x32_bf16 v[48:51], v[178:181], v[186:189], 0
	v_mfma_f32_16x16x32_bf16 v[40:43], v[170:173], v[194:197], 0
	v_mfma_f32_16x16x32_bf16 v[32:35], v[178:181], v[194:197], 0
	v_mfma_f32_16x16x32_bf16 v[24:27], v[170:173], v[202:205], 0
	v_mfma_f32_16x16x32_bf16 v[16:19], v[178:181], v[202:205], 0
	v_mfma_f32_16x16x32_bf16 v[8:11], v[170:173], v[210:213], 0
	v_mfma_f32_16x16x32_bf16 v[0:3], v[178:181], v[210:213], 0
	v_mfma_f32_16x16x32_bf16 v[56:59], v[174:177], v[190:193], v[56:59]
	v_mfma_f32_16x16x32_bf16 v[48:51], v[182:185], v[190:193], v[48:51]
	v_mfma_f32_16x16x32_bf16 v[40:43], v[174:177], v[198:201], v[40:43]
	v_mfma_f32_16x16x32_bf16 v[32:35], v[182:185], v[198:201], v[32:35]
	v_mfma_f32_16x16x32_bf16 v[24:27], v[174:177], v[206:209], v[24:27]
	v_mfma_f32_16x16x32_bf16 v[16:19], v[182:185], v[206:209], v[16:19]
	v_mfma_f32_16x16x32_bf16 v[8:11], v[174:177], v[214:217], v[8:11]
	v_mfma_f32_16x16x32_bf16 v[0:3], v[182:185], v[214:217], v[0:3]
	s_barrier
; #define PG8_STAGE(bufoff, gbase, voff) do { _Pragma("unroll") for (int _i = 0; _i < 2; ++_i) \
;         __builtin_amdgcn_global_load_lds((const unsigned*)((const char*)(gbase) + (voff)[_i]), (PG8_LAS unsigned*)(lds + (bufoff) + ldsw + _i * 8192), 16, 0, 0); } while (0)
; #define PG8_LDA(dst, b, h) do { _Pragma("unroll") for (int m = 0; m < 4; ++m) _Pragma("unroll") for (int k = 0; k < 2; ++k) dst[m][k] = *(const PG8_LAS bf16x8*)(lds + PG8_SA(b, h) + aoff + m * 2048 + k * 1024); } while (0)
; #define PG8_LDB(dst, b, h) do { _Pragma("unroll") for (int n = 0; n < 2; ++n) _Pragma("unroll") for (int k = 0; k < 2; ++k) dst[n][k] = *(const PG8_LAS bf16x8*)(lds + PG8_SB(b, h) + boff + n * 2048 + k * 1024); } while (0)
; #define PG8_MMA(ai, bj, At, Bt) do { __builtin_amdgcn_s_setprio(1); _Pragma("unroll") for (int m = 0; m < 4; ++m) _Pragma("unroll") for (int n = 0; n < 2; ++n) _Pragma("unroll") for (int k = 0; k < 2; ++k) \
;         acc[ai][bj][m][n] = __builtin_amdgcn_mfma_f32_16x16x32_bf16(Bt[n][k], At[m][k], acc[ai][bj][m][n], 0, 0, 0); __builtin_amdgcn_s_setprio(0); } while (0)
; #define PG8_WAIT_V(n) asm volatile("s_waitcnt vmcnt(" #n ")" ::: "memory")
; #define PG8_WAIT_L(n) asm volatile("s_waitcnt lgkmcnt(" #n ")" ::: "memory")
; #define PG8_BAR __builtin_amdgcn_s_barrier()
; #define PG8_SCHED __builtin_amdgcn_sched_barrier(0)
; template <class Epi, class Sched, bool ALIGN_EPI = false, bool SP2 = false>
; __device__ __forceinline__ void gemm_phase(PG8_LAS unsigned char* lds, const Gemm g, const Sched& S, const Epi& E) {
;     ...
;             PG8_LDB(B0, 1, 0); PG8_LDB(B1, 1, 1); PG8_SCHED; PG8_LDA(At, 1, 0); PG8_STAGE(PG8_SA(0, 1), a2 + hstep, voffA);
;             PG8_WAIT_V(8); PG8_WAIT_L(0); PG8_BAR; PG8_MMA(0, 0, At, B0); PG8_MMA(0, 1, At, B1); PG8_BAR; PG8_SCHED;
;             PG8_LDA(At, 1, 1); PG8_STAGE(PG8_SB(1, 0), b3, voffB); PG8_STAGE(PG8_SB(1, 1), b3 + hstep, voffB); PG8_STAGE(PG8_SA(1, 0), a3, voffA);
;             PG8_WAIT_V(8); PG8_WAIT_L(0); PG8_BAR; PG8_MMA(1, 0, At, B0); PG8_MMA(1, 1, At, B1); PG8_BAR; PG8_SCHED;
	s_setprio 0
	s_add_i32 s69, 0, 0x18000
	v_add_u32_e32 v153, s69, v147
	s_add_i32 s70, 0, 0x1c000
	ds_read_b128 v[154:157], v153
	ds_read_b128 v[158:161], v153 offset:1024
	ds_read_b128 v[162:165], v153 offset:2048
	ds_read_b128 v[166:169], v153 offset:3072
	v_add_u32_e32 v153, s70, v147
	ds_read_b128 v[170:173], v153
	ds_read_b128 v[174:177], v153 offset:1024
	ds_read_b128 v[178:181], v153 offset:2048
	ds_read_b128 v[182:185], v153 offset:3072
	s_add_u32 s42, s42, 0x40000
	s_addc_u32 s43, s43, 0
	s_mov_b32 m0, s51
	v_lshl_add_u64 v[224:225], s[42:43], 0, v[134:135]
	ds_read_b128 v[186:189], v151 offset:32768
	ds_read_b128 v[190:193], v151 offset:33792
	ds_read_b128 v[194:197], v151 offset:34816
	ds_read_b128 v[198:201], v151 offset:35840
	ds_read_b128 v[202:205], v151 offset:36864
	ds_read_b128 v[206:209], v151 offset:37888
	ds_read_b128 v[210:213], v151 offset:38912
	ds_read_b128 v[214:217], v151 offset:39936
	global_load_lds_dwordx4 v[224:225], off
	v_lshl_add_u64 v[224:225], s[42:43], 0, v[130:131]
	s_mov_b32 m0, s52
	s_nop 0
	global_load_lds_dwordx4 v[224:225], off
	s_waitcnt vmcnt(8)
	s_waitcnt lgkmcnt(0)
	s_barrier
	s_setprio 1
	v_mfma_f32_16x16x32_bf16 v[120:123], v[154:157], v[186:189], v[120:123]
	v_mfma_f32_16x16x32_bf16 v[116:119], v[162:165], v[186:189], v[116:119]
	v_mfma_f32_16x16x32_bf16 v[108:111], v[154:157], v[194:197], v[108:111]
	v_mfma_f32_16x16x32_bf16 v[100:103], v[162:165], v[194:197], v[100:103]
	v_mfma_f32_16x16x32_bf16 v[92:95], v[154:157], v[202:205], v[92:95]
	v_mfma_f32_16x16x32_bf16 v[84:87], v[162:165], v[202:205], v[84:87]
	v_mfma_f32_16x16x32_bf16 v[76:79], v[154:157], v[210:213], v[76:79]
	v_mfma_f32_16x16x32_bf16 v[68:71], v[162:165], v[210:213], v[68:71]
	v_mfma_f32_16x16x32_bf16 v[120:123], v[158:161], v[190:193], v[120:123]
	v_mfma_f32_16x16x32_bf16 v[116:119], v[166:169], v[190:193], v[116:119]
	v_mfma_f32_16x16x32_bf16 v[108:111], v[158:161], v[198:201], v[108:111]
	v_mfma_f32_16x16x32_bf16 v[100:103], v[166:169], v[198:201], v[100:103]
	v_mfma_f32_16x16x32_bf16 v[92:95], v[158:161], v[206:209], v[92:95]
	v_mfma_f32_16x16x32_bf16 v[84:87], v[166:169], v[206:209], v[84:87]
	v_mfma_f32_16x16x32_bf16 v[76:79], v[158:161], v[214:217], v[76:79]
	v_mfma_f32_16x16x32_bf16 v[68:71], v[166:169], v[214:217], v[68:71]
	v_mfma_f32_16x16x32_bf16 v[124:127], v[170:173], v[186:189], v[124:127]
	v_mfma_f32_16x16x32_bf16 v[112:115], v[178:181], v[186:189], v[112:115]
	v_mfma_f32_16x16x32_bf16 v[104:107], v[170:173], v[194:197], v[104:107]
	v_mfma_f32_16x16x32_bf16 v[96:99], v[178:181], v[194:197], v[96:99]
	v_mfma_f32_16x16x32_bf16 v[88:91], v[170:173], v[202:205], v[88:91]
	v_mfma_f32_16x16x32_bf16 v[80:83], v[178:181], v[202:205], v[80:83]
	v_mfma_f32_16x16x32_bf16 v[72:75], v[170:173], v[210:213], v[72:75]
	v_mfma_f32_16x16x32_bf16 v[64:67], v[178:181], v[210:213], v[64:67]
	v_mfma_f32_16x16x32_bf16 v[124:127], v[174:177], v[190:193], v[124:127]
	v_mfma_f32_16x16x32_bf16 v[112:115], v[182:185], v[190:193], v[112:115]
	v_mfma_f32_16x16x32_bf16 v[104:107], v[174:177], v[198:201], v[104:107]
	v_mfma_f32_16x16x32_bf16 v[96:99], v[182:185], v[198:201], v[96:99]
	v_mfma_f32_16x16x32_bf16 v[88:91], v[174:177], v[206:209], v[88:91]
	v_mfma_f32_16x16x32_bf16 v[80:83], v[182:185], v[206:209], v[80:83]
	v_mfma_f32_16x16x32_bf16 v[72:75], v[174:177], v[214:217], v[72:75]
	v_mfma_f32_16x16x32_bf16 v[64:67], v[182:185], v[214:217], v[64:67]
	s_barrier
	s_setprio 0
	s_add_i32 s42, s69, s48
	v_lshl_add_u64 v[144:145], v[144:145], 0, s[14:15]
	s_mov_b32 m0, s42
	ds_read_b128 v[186:189], v151 offset:49152
	ds_read_b128 v[190:193], v151 offset:50176
	ds_read_b128 v[194:197], v151 offset:51200
	ds_read_b128 v[198:201], v151 offset:52224
	ds_read_b128 v[202:205], v151 offset:53248
	ds_read_b128 v[206:209], v151 offset:54272
	ds_read_b128 v[210:213], v151 offset:55296
	ds_read_b128 v[214:217], v151 offset:56320
	global_load_lds_dwordx4 v[144:145], off
	s_add_i32 m0, s42, 0x2000
	s_add_u32 s40, s40, 0x40080
	v_lshl_add_u64 v[144:145], v[218:219], 0, s[14:15]
	s_addc_u32 s41, s41, 0
	s_add_i32 s42, s70, s48
	global_load_lds_dwordx4 v[144:145], off
	v_lshl_add_u64 v[144:145], s[40:41], 0, v[132:133]
	s_mov_b32 m0, s42
	s_nop 0
	global_load_lds_dwordx4 v[144:145], off
	v_lshl_add_u64 v[144:145], s[40:41], 0, v[128:129]
	s_add_i32 m0, s42, 0x2000
	s_nop 0
	global_load_lds_dwordx4 v[144:145], off
	v_lshl_add_u64 v[144:145], v[220:221], 0, s[14:15]
	s_mov_b32 m0, s53
	s_nop 0
	global_load_lds_dwordx4 v[144:145], off
	v_lshl_add_u64 v[144:145], v[222:223], 0, s[14:15]
	s_mov_b32 m0, s54
	s_nop 0
	global_load_lds_dwordx4 v[144:145], off
	s_waitcnt vmcnt(8)
	s_waitcnt lgkmcnt(0)
	s_barrier
	s_setprio 1
	v_mfma_f32_16x16x32_bf16 v[60:63], v[154:157], v[186:189], v[60:63]
	v_mfma_f32_16x16x32_bf16 v[52:55], v[162:165], v[186:189], v[52:55]
	v_mfma_f32_16x16x32_bf16 v[44:47], v[154:157], v[194:197], v[44:47]
	v_mfma_f32_16x16x32_bf16 v[36:39], v[162:165], v[194:197], v[36:39]
	v_mfma_f32_16x16x32_bf16 v[28:31], v[154:157], v[202:205], v[28:31]
	v_mfma_f32_16x16x32_bf16 v[20:23], v[162:165], v[202:205], v[20:23]
	v_mfma_f32_16x16x32_bf16 v[12:15], v[154:157], v[210:213], v[12:15]
	v_mfma_f32_16x16x32_bf16 v[4:7], v[162:165], v[210:213], v[4:7]
	v_mfma_f32_16x16x32_bf16 v[60:63], v[158:161], v[190:193], v[60:63]
	v_mfma_f32_16x16x32_bf16 v[52:55], v[166:169], v[190:193], v[52:55]
	v_mfma_f32_16x16x32_bf16 v[44:47], v[158:161], v[198:201], v[44:47]
	v_mfma_f32_16x16x32_bf16 v[36:39], v[166:169], v[198:201], v[36:39]
	v_mfma_f32_16x16x32_bf16 v[28:31], v[158:161], v[206:209], v[28:31]
	v_mfma_f32_16x16x32_bf16 v[20:23], v[166:169], v[206:209], v[20:23]
	v_mfma_f32_16x16x32_bf16 v[12:15], v[158:161], v[214:217], v[12:15]
	v_mfma_f32_16x16x32_bf16 v[4:7], v[166:169], v[214:217], v[4:7]
	v_mfma_f32_16x16x32_bf16 v[56:59], v[170:173], v[186:189], v[56:59]
	v_mfma_f32_16x16x32_bf16 v[48:51], v[178:181], v[186:189], v[48:51]
	v_mfma_f32_16x16x32_bf16 v[40:43], v[170:173], v[194:197], v[40:43]
	v_mfma_f32_16x16x32_bf16 v[32:35], v[178:181], v[194:197], v[32:35]
	v_mfma_f32_16x16x32_bf16 v[24:27], v[170:173], v[202:205], v[24:27]
	v_mfma_f32_16x16x32_bf16 v[16:19], v[178:181], v[202:205], v[16:19]
	v_mfma_f32_16x16x32_bf16 v[8:11], v[170:173], v[210:213], v[8:11]
	v_mfma_f32_16x16x32_bf16 v[0:3], v[178:181], v[210:213], v[0:3]
	v_mfma_f32_16x16x32_bf16 v[56:59], v[174:177], v[190:193], v[56:59]
	v_mfma_f32_16x16x32_bf16 v[48:51], v[182:185], v[190:193], v[48:51]
	v_mfma_f32_16x16x32_bf16 v[40:43], v[174:177], v[198:201], v[40:43]
	v_mfma_f32_16x16x32_bf16 v[32:35], v[182:185], v[198:201], v[32:35]
	v_mfma_f32_16x16x32_bf16 v[24:27], v[174:177], v[206:209], v[24:27]
	v_mfma_f32_16x16x32_bf16 v[16:19], v[182:185], v[206:209], v[16:19]
	v_mfma_f32_16x16x32_bf16 v[8:11], v[174:177], v[214:217], v[8:11]
	v_mfma_f32_16x16x32_bf16 v[0:3], v[182:185], v[214:217], v[0:3]
	s_barrier
	s_setprio 0
	s_add_i32 s68, s68, 2
	s_add_u32 s38, s38, 0x100
	s_addc_u32 s39, s39, 0
	s_add_u32 s66, s66, 0x100
	s_addc_u32 s67, s67, 0
